# attention A loop: row-sum accumulation adds pairs first (breaks the back-to-back dependent add chain)
# baseline (speedup 1.0000x reference)
; #define FA_SB() __builtin_amdgcn_sched_barrier(0)
; #define FA_EXP2(J, PX, R) do { const float e0_ = __builtin_amdgcn_exp2f(PX[R]), e1_ = __builtin_amdgcn_exp2f(PX[(R) + 1]); ps += e0_; ps += e1_; PWN[(J) >> 2][(J) & 3] = cvtpk(e0_, e1_); } while (0)
; __device__ __forceinline__ void attn_unit_a(FLAS unsigned char* lds, const Unit u) {
;     ...
;         if (ziN) { pN0 = __builtin_amdgcn_mfma_f32_32x32x16_bf16(kf[0], qr[0], z16, 0, 0, 0); FA_EXP2(8, pC1, 0); FA_SB(); pN1 = __builtin_amdgcn_mfma_f32_32x32x16_bf16(kf[1], qr[0], z16, 0, 0, 0); }
;         else { pN0 = __builtin_amdgcn_mfma_f32_32x32x16_bf16(kf[0], qr[0], pN0, 0, 0, 0); FA_EXP2(8, pC1, 0); FA_SB(); pN1 = __builtin_amdgcn_mfma_f32_32x32x16_bf16(kf[1], qr[0], pN1, 0, 0, 0); }
.Lgather_e:
	v_add_u32_e32 v76, s49, v210
	v_add_u32_e32 v64, 0x17600, v76
	v_add_u32_e32 v66, 0x17680, v76
	v_add_u32_e32 v67, 0x17608, v76
	v_add_u32_e32 v68, 0x17688, v76
	ds_read2_b32 v[64:65], v64 offset1:1
	ds_read2_b32 v[80:81], v66 offset1:1
	ds_read2_b32 v[66:67], v67 offset1:1
	ds_read2_b32 v[82:83], v68 offset1:1
	v_add_u32_e32 v68, 0x17620, v76
	v_add_u32_e32 v70, 0x176a0, v76
	v_add_u32_e32 v71, 0x17628, v76
	v_add_u32_e32 v72, 0x176a8, v76
	ds_read2_b32 v[68:69], v68 offset1:1
	ds_read2_b32 v[84:85], v70 offset1:1
	ds_read2_b32 v[70:71], v71 offset1:1
	ds_read2_b32 v[86:87], v72 offset1:1
	v_add_u32_e32 v72, 0x17640, v76
	v_add_u32_e32 v74, 0x176c0, v76
	v_add_u32_e32 v75, 0x17648, v76
	v_add_u32_e32 v77, 0x176c8, v76
	ds_read2_b32 v[72:73], v72 offset1:1
	ds_read2_b32 v[88:89], v74 offset1:1
	ds_read2_b32 v[74:75], v75 offset1:1
	ds_read2_b32 v[90:91], v77 offset1:1
	v_add_u32_e32 v77, 0x17660, v76
	v_add_u32_e32 v78, 0x176e0, v76
	v_add_u32_e32 v79, 0x17668, v76
	v_add_u32_e32 v94, 0x176e8, v76
	ds_read2_b32 v[76:77], v77 offset1:1
	ds_read2_b32 v[92:93], v78 offset1:1
	ds_read2_b32 v[78:79], v79 offset1:1
	ds_read2_b32 v[94:95], v94 offset1:1
	s_waitcnt lgkmcnt(0)
	v_sub_f32_e32 v64, v64, v211
	v_sub_f32_e32 v65, v65, v211
	v_sub_f32_e32 v66, v66, v211
	v_sub_f32_e32 v67, v67, v211
	v_sub_f32_e32 v68, v68, v211
	v_sub_f32_e32 v69, v69, v211
	v_sub_f32_e32 v70, v70, v211
	v_sub_f32_e32 v71, v71, v211
	v_sub_f32_e32 v72, v72, v211
	v_sub_f32_e32 v73, v73, v211
	v_sub_f32_e32 v74, v74, v211
	v_sub_f32_e32 v75, v75, v211
	v_sub_f32_e32 v76, v76, v211
	v_sub_f32_e32 v77, v77, v211
	v_sub_f32_e32 v78, v78, v211
	v_sub_f32_e32 v79, v79, v211
	v_sub_f32_e32 v80, v80, v211
	v_sub_f32_e32 v81, v81, v211
	v_sub_f32_e32 v82, v82, v211
	v_sub_f32_e32 v83, v83, v211
	v_sub_f32_e32 v84, v84, v211
	v_sub_f32_e32 v85, v85, v211
	v_sub_f32_e32 v86, v86, v211
	v_sub_f32_e32 v87, v87, v211
	v_sub_f32_e32 v88, v88, v211
	v_sub_f32_e32 v89, v89, v211
	v_sub_f32_e32 v90, v90, v211
	v_sub_f32_e32 v91, v91, v211
	v_sub_f32_e32 v92, v92, v211
	v_sub_f32_e32 v93, v93, v211
	v_sub_f32_e32 v94, v94, v211
	v_sub_f32_e32 v95, v95, v211
	s_nop 1
	v_mfma_f32_32x32x16_bf16 v[64:79], v[204:207], v[160:163], v[64:79]
	v_exp_f32_e32 v112, v112
	v_exp_f32_e32 v113, v113
	v_add_f32_e32 v190, v110, v111
	v_add_f32_e32 v212, v190, v212
	v_mfma_f32_32x32x16_bf16 v[80:95], v[200:203], v[160:163], v[80:95]
	v_exp_f32_e32 v114, v114
	v_exp_f32_e32 v115, v115
	s_branch .Lk2_e

; #define FA_SB() __builtin_amdgcn_sched_barrier(0)
; #define FA_EXP2(J, PX, R) do { const float e0_ = __builtin_amdgcn_exp2f(PX[R]), e1_ = __builtin_amdgcn_exp2f(PX[(R) + 1]); ps += e0_; ps += e1_; PWN[(J) >> 2][(J) & 3] = cvtpk(e0_, e1_); } while (0)
; __device__ __forceinline__ void attn_unit_a(FLAS unsigned char* lds, const Unit u) {
;     ...
;         if (ziN) { pN0 = __builtin_amdgcn_mfma_f32_32x32x16_bf16(kf[0], qr[0], z16, 0, 0, 0); FA_EXP2(8, pC1, 0); FA_SB(); pN1 = __builtin_amdgcn_mfma_f32_32x32x16_bf16(kf[1], qr[0], z16, 0, 0, 0); }
;         else { pN0 = __builtin_amdgcn_mfma_f32_32x32x16_bf16(kf[0], qr[0], pN0, 0, 0, 0); FA_EXP2(8, pC1, 0); FA_SB(); pN1 = __builtin_amdgcn_mfma_f32_32x32x16_bf16(kf[1], qr[0], pN1, 0, 0, 0); }
.Lgather_o:
	v_sub_u32_e32 v96, s12, v244
	v_lshl_add_u32 v108, v96, 2, v240
	v_add_u32_e32 v96, 0x1500, v108
	v_add_u32_e32 v98, 0x1580, v108
	v_add_u32_e32 v99, 0x1508, v108
	v_add_u32_e32 v100, 0x1588, v108
	ds_read2_b32 v[96:97], v96 offset1:1
	ds_read2_b32 v[112:113], v98 offset1:1
	ds_read2_b32 v[98:99], v99 offset1:1
	ds_read2_b32 v[114:115], v100 offset1:1
	v_add_u32_e32 v100, 0x1520, v108
	v_add_u32_e32 v102, 0x15a0, v108
	v_add_u32_e32 v103, 0x1528, v108
	v_add_u32_e32 v104, 0x15a8, v108
	ds_read2_b32 v[100:101], v100 offset1:1
	ds_read2_b32 v[116:117], v102 offset1:1
	ds_read2_b32 v[102:103], v103 offset1:1
	ds_read2_b32 v[118:119], v104 offset1:1
	v_add_u32_e32 v104, 0x1540, v108
	v_add_u32_e32 v106, 0x15c0, v108
	v_add_u32_e32 v107, 0x1548, v108
	v_add_u32_e32 v109, 0x15c8, v108
	ds_read2_b32 v[104:105], v104 offset1:1
	ds_read2_b32 v[120:121], v106 offset1:1
	ds_read2_b32 v[106:107], v107 offset1:1
	ds_read2_b32 v[122:123], v109 offset1:1
	v_add_u32_e32 v109, 0x1560, v108
	v_add_u32_e32 v110, 0x15e0, v108
	v_add_u32_e32 v111, 0x1568, v108
	v_add_u32_e32 v126, 0x15e8, v108
	ds_read2_b32 v[108:109], v109 offset1:1
	ds_read2_b32 v[124:125], v110 offset1:1
	ds_read2_b32 v[110:111], v111 offset1:1
	ds_read2_b32 v[126:127], v126 offset1:1
	s_waitcnt lgkmcnt(0)
	v_sub_f32_e32 v96, v96, v211
	v_sub_f32_e32 v97, v97, v211
	v_sub_f32_e32 v98, v98, v211
	v_sub_f32_e32 v99, v99, v211
	v_sub_f32_e32 v100, v100, v211
	v_sub_f32_e32 v101, v101, v211
	v_sub_f32_e32 v102, v102, v211
	v_sub_f32_e32 v103, v103, v211
	v_sub_f32_e32 v104, v104, v211
	v_sub_f32_e32 v105, v105, v211
	v_sub_f32_e32 v106, v106, v211
	v_sub_f32_e32 v107, v107, v211
	v_sub_f32_e32 v108, v108, v211
	v_sub_f32_e32 v109, v109, v211
	v_sub_f32_e32 v110, v110, v211
	v_sub_f32_e32 v111, v111, v211
	v_sub_f32_e32 v112, v112, v211
	v_sub_f32_e32 v113, v113, v211
	v_sub_f32_e32 v114, v114, v211
	v_sub_f32_e32 v115, v115, v211
	v_sub_f32_e32 v116, v116, v211
	v_sub_f32_e32 v117, v117, v211
	v_sub_f32_e32 v118, v118, v211
	v_sub_f32_e32 v119, v119, v211
	v_sub_f32_e32 v120, v120, v211
	v_sub_f32_e32 v121, v121, v211
	v_sub_f32_e32 v122, v122, v211
	v_sub_f32_e32 v123, v123, v211
	v_sub_f32_e32 v124, v124, v211
	v_sub_f32_e32 v125, v125, v211
	v_sub_f32_e32 v126, v126, v211
	v_sub_f32_e32 v127, v127, v211
	s_nop 1
	v_mfma_f32_32x32x16_bf16 v[96:111], v[200:203], v[160:163], v[96:111]
	v_exp_f32_e32 v80, v80
	v_exp_f32_e32 v81, v81
	v_add_f32_e32 v206, v78, v79
	v_add_f32_e32 v212, v206, v212
	v_mfma_f32_32x32x16_bf16 v[112:127], v[196:199], v[160:163], v[112:127]
	v_exp_f32_e32 v82, v82
	v_exp_f32_e32 v83, v83
	s_branch .Lk2_o

; #define FA_SB() __builtin_amdgcn_sched_barrier(0)
; __device__ __forceinline__ void attn_unit_a(FLAS unsigned char* lds, const Unit u) {
;     ...
;         FA_PVM(0); pC0[0] = fadd_s(pC0[0], off); pC1[0] = fadd_s(pC1[0], off); pC0[1] = fadd_s(pC0[1], off); pC1[1] = fadd_s(pC1[1], off); pC0[2] = fadd_s(pC0[2], off); pC1[2] = fadd_s(pC1[2], off); FA_SB();
;         FA_PVM(1); ra = __builtin_fmaxf(__builtin_fmaxf(pC0[0], pC0[1]), pC0[2]); rb = __builtin_fmaxf(__builtin_fmaxf(pC1[0], pC1[1]), pC1[2]); pC0[3] = fadd_s(pC0[3], off); pC1[3] = fadd_s(pC1[3], off); pC0[4] = fadd_s(pC0[4], off); pC1[4] = fadd_s(pC1[4], off); FA_SB();
;         FA_PVM(2); ra = __builtin_fmaxf(__builtin_fmaxf(ra, pC0[3]), pC0[4]); rb = __builtin_fmaxf(__builtin_fmaxf(rb, pC1[3]), pC1[4]); pC0[5] = fadd_s(pC0[5], off); pC1[5] = fadd_s(pC1[5], off); pC0[6] = fadd_s(pC0[6], off); pC1[6] = fadd_s(pC1[6], off); FA_SB();
;         FA_PVM(3); ra = __builtin_fmaxf(__builtin_fmaxf(ra, pC0[5]), pC0[6]); rb = __builtin_fmaxf(__builtin_fmaxf(rb, pC1[5]), pC1[6]); pC0[7] = fadd_s(pC0[7], off); pC1[7] = fadd_s(pC1[7], off); pC0[8] = fadd_s(pC0[8], off); pC1[8] = fadd_s(pC1[8], off); FA_SB();
;         FA_PVM(4); ra = __builtin_fmaxf(__builtin_fmaxf(ra, pC0[7]), pC0[8]); rb = __builtin_fmaxf(__builtin_fmaxf(rb, pC1[7]), pC1[8]); pC0[9] = fadd_s(pC0[9], off); pC1[9] = fadd_s(pC1[9], off); pC0[10] = fadd_s(pC0[10], off); pC1[10] = fadd_s(pC1[10], off); FA_SB();
;         FA_PVM(5); ra = __builtin_fmaxf(__builtin_fmaxf(ra, pC0[9]), pC0[10]); rb = __builtin_fmaxf(__builtin_fmaxf(rb, pC1[9]), pC1[10]); pC0[11] = fadd_s(pC0[11], off); pC1[11] = fadd_s(pC1[11], off); pC0[12] = fadd_s(pC0[12], off); pC1[12] = fadd_s(pC1[12], off); FA_SB();
;         FA_PVM(6); ra = __builtin_fmaxf(__builtin_fmaxf(ra, pC0[11]), pC0[12]); rb = __builtin_fmaxf(__builtin_fmaxf(rb, pC1[11]), pC1[12]); pC0[13] = fadd_s(pC0[13], off); pC1[13] = fadd_s(pC1[13], off); pC0[14] = fadd_s(pC0[14], off); pC1[14] = fadd_s(pC1[14], off); FA_SB();
;         FA_PVM(7); ra = __builtin_fmaxf(__builtin_fmaxf(ra, pC0[13]), pC0[14]); rb = __builtin_fmaxf(__builtin_fmaxf(rb, pC1[13]), pC1[14]); pC0[15] = fadd_s(pC0[15], off); pC1[15] = fadd_s(pC1[15], off); ra = __builtin_fmaxf(__builtin_fmaxf(ra, pC0[15]), pC1[15]); rm = __builtin_fmaxf(ra, rb); FA_SB();
;         rm = xhalf_max(rm);
;         FA_SB();
;         if (first || __any(rm > 8.0f)) {
.LBB0_437:
	v_max3_f32 v140, v96, v97, v98
	v_max3_f32 v141, v112, v113, v114
	v_cvt_pk_bf16_f32 v196, v72, v73
	v_cvt_pk_bf16_f32 v197, v74, v75
	v_add_f32_e32 v142, v80, v81
	v_add_f32_e32 v212, v142, v212
	v_mfma_f32_32x32x16_bf16 v[32:47], v[132:135], v[204:207], v[32:47]
	ds_read_b128 v[132:135], v200 offset:16416
	v_max3_f32 v140, v140, v99, v100
	v_max3_f32 v141, v141, v115, v116
	v_cvt_pk_bf16_f32 v198, v76, v77
	v_cvt_pk_bf16_f32 v199, v78, v79
	v_add_f32_e32 v142, v82, v83
	v_add_f32_e32 v212, v142, v212
	s_waitcnt lgkmcnt(1)
	v_mfma_f32_32x32x16_bf16 v[16:31], v[136:139], v[204:207], v[16:31]
	ds_read_b128 v[136:139], v200 offset:21024
	v_max3_f32 v140, v140, v101, v102
	v_max3_f32 v141, v141, v117, v118
	v_cvt_pk_bf16_f32 v192, v80, v81
	v_cvt_pk_bf16_f32 v193, v82, v83
	v_add_f32_e32 v142, v84, v85
	v_add_f32_e32 v212, v142, v212
	v_mfma_f32_32x32x16_bf16 v[0:15], v[128:131], v[204:207], v[0:15]
	ds_read_b128 v[128:131], v200 offset:25632
	v_max3_f32 v140, v140, v103, v104
	v_max3_f32 v141, v141, v119, v120
	v_cvt_pk_bf16_f32 v194, v84, v85
	v_cvt_pk_bf16_f32 v195, v86, v87
	v_add_f32_e32 v142, v86, v87
	v_add_f32_e32 v212, v142, v212
	s_waitcnt lgkmcnt(1)
	v_mfma_f32_32x32x16_bf16 v[48:63], v[132:135], v[196:199], v[48:63]
	ds_read_b128 v[132:135], v200 offset:30240
	v_max3_f32 v140, v140, v105, v106
	v_max3_f32 v141, v141, v121, v122
	v_cvt_pk_bf16_f32 v188, v88, v89
	v_cvt_pk_bf16_f32 v189, v90, v91
	v_add_f32_e32 v142, v88, v89
	v_add_f32_e32 v212, v142, v212
	v_mfma_f32_32x32x16_bf16 v[32:47], v[136:139], v[196:199], v[32:47]
	ds_read_b128 v[136:139], v200 offset:16448
	v_max3_f32 v140, v140, v107, v108
	v_max3_f32 v141, v141, v123, v124
	v_cvt_pk_bf16_f32 v190, v92, v93
	v_cvt_pk_bf16_f32 v191, v94, v95
	v_add_f32_e32 v142, v90, v91
	v_add_f32_e32 v212, v142, v212
	s_waitcnt lgkmcnt(1)
	v_mfma_f32_32x32x16_bf16 v[16:31], v[128:131], v[196:199], v[16:31]
	ds_read_b128 v[128:131], v200 offset:21056
	v_max3_f32 v140, v140, v109, v110
	v_max3_f32 v141, v141, v125, v126
	v_add_f32_e32 v142, v92, v93
	v_add_f32_e32 v212, v142, v212
	v_mfma_f32_32x32x16_bf16 v[0:15], v[132:135], v[196:199], v[0:15]
	ds_read_b128 v[132:135], v200 offset:25664
	v_max3_f32 v140, v140, v141, v111
	v_max_f32_e32 v140, v140, v127
	v_add_f32_e32 v142, v94, v95
	v_add_f32_e32 v212, v142, v212
	s_andn2_b64 vcc, exec, s[20:21]
	s_cbranch_vccnz .LBB0_440
	v_cmp_lt_f32_e32 vcc, s39, v140
	s_cbranch_vccnz .Lresc_e
	s_mov_b64 s[20:21], 0
.LBB0_442:
	s_waitcnt lgkmcnt(1)
	v_mfma_f32_32x32x16_bf16 v[48:63], v[136:139], v[192:195], v[48:63]
	ds_read_b128 v[136:139], v200 offset:30272
	v_exp_f32_e32 v96, v96
	v_exp_f32_e32 v97, v97
	v_mfma_f32_32x32x16_bf16 v[32:47], v[128:131], v[192:195], v[32:47]
	ds_read_b128 v[128:131], v200 offset:16480
	v_exp_f32_e32 v98, v98
	v_exp_f32_e32 v99, v99
	v_add_f32_e32 v142, v96, v97
	v_add_f32_e32 v212, v142, v212
	s_waitcnt lgkmcnt(1)
	v_mfma_f32_32x32x16_bf16 v[16:31], v[132:135], v[192:195], v[16:31]
	ds_read_b128 v[132:135], v200 offset:21088
	v_exp_f32_e32 v100, v100
	v_exp_f32_e32 v101, v101
	v_add_f32_e32 v142, v98, v99
	v_add_f32_e32 v212, v142, v212
	v_mfma_f32_32x32x16_bf16 v[0:15], v[136:139], v[192:195], v[0:15]
	ds_read_b128 v[136:139], v200 offset:25696
	v_exp_f32_e32 v102, v102
	v_exp_f32_e32 v103, v103
	v_add_f32_e32 v142, v100, v101
	v_add_f32_e32 v212, v142, v212
	s_waitcnt lgkmcnt(1)
	v_mfma_f32_32x32x16_bf16 v[48:63], v[128:131], v[188:191], v[48:63]
	ds_read_b128 v[128:131], v200 offset:30304
	ds_read_b128 v[204:207], v247 offset:8192
	ds_read_b128 v[200:203], v247 offset:8704
	ds_read_b128 v[196:199], v248 offset:8192
	ds_read_b128 v[192:195], v248 offset:8704
	v_exp_f32_e32 v104, v104
	v_exp_f32_e32 v105, v105
	v_add_f32_e32 v142, v102, v103
	v_add_f32_e32 v212, v142, v212
	v_mfma_f32_32x32x16_bf16 v[32:47], v[132:135], v[188:191], v[32:47]
	v_exp_f32_e32 v106, v106
	v_exp_f32_e32 v107, v107
	v_add_f32_e32 v142, v104, v105
	v_add_f32_e32 v212, v142, v212
	s_waitcnt lgkmcnt(4)
	v_mfma_f32_32x32x16_bf16 v[16:31], v[136:139], v[188:191], v[16:31]
	v_exp_f32_e32 v108, v108
	v_exp_f32_e32 v109, v109
	v_add_f32_e32 v142, v106, v107
	v_add_f32_e32 v212, v142, v212
	v_mfma_f32_32x32x16_bf16 v[0:15], v[128:131], v[188:191], v[0:15]
	v_exp_f32_e32 v110, v110
	v_exp_f32_e32 v111, v111
	v_add_f32_e32 v142, v108, v109
	v_add_f32_e32 v212, v142, v212
	s_sub_i32 s12, s48, 31
	s_cmpk_lt_i32 s12, 0x22f
	s_cselect_b32 s98, s100, s101
	s_cselect_b32 s15, 1, 0
	s_cmpk_gt_i32 s48, 0xfd92
	s_cselect_b32 s15, s15, 0
	s_cmp_lg_u32 s15, 0
	s_cbranch_scc1 .Lgather_e
	s_cmp_lg_u32 s99, s98
	s_cbranch_scc1 .Lz_upd_e
.Lz_go_e:
	s_waitcnt lgkmcnt(0)
	v_mfma_f32_32x32x16_bf16 v[64:79], v[204:207], v[160:163], v[144:159]
	v_exp_f32_e32 v112, v112
	v_exp_f32_e32 v113, v113
	v_add_f32_e32 v190, v110, v111
	v_add_f32_e32 v212, v190, v212
	v_mfma_f32_32x32x16_bf16 v[80:95], v[200:203], v[160:163], v[144:159]
	v_exp_f32_e32 v114, v114
	v_exp_f32_e32 v115, v115

; #define FA_SB() __builtin_amdgcn_sched_barrier(0)
; __device__ __forceinline__ void attn_unit_a(FLAS unsigned char* lds, const Unit u) {
;     ...
;         FA_PVM(0); pC0[0] = fadd_s(pC0[0], off); pC1[0] = fadd_s(pC1[0], off); pC0[1] = fadd_s(pC0[1], off); pC1[1] = fadd_s(pC1[1], off); pC0[2] = fadd_s(pC0[2], off); pC1[2] = fadd_s(pC1[2], off); FA_SB();
;         FA_PVM(1); ra = __builtin_fmaxf(__builtin_fmaxf(pC0[0], pC0[1]), pC0[2]); rb = __builtin_fmaxf(__builtin_fmaxf(pC1[0], pC1[1]), pC1[2]); pC0[3] = fadd_s(pC0[3], off); pC1[3] = fadd_s(pC1[3], off); pC0[4] = fadd_s(pC0[4], off); pC1[4] = fadd_s(pC1[4], off); FA_SB();
;         FA_PVM(2); ra = __builtin_fmaxf(__builtin_fmaxf(ra, pC0[3]), pC0[4]); rb = __builtin_fmaxf(__builtin_fmaxf(rb, pC1[3]), pC1[4]); pC0[5] = fadd_s(pC0[5], off); pC1[5] = fadd_s(pC1[5], off); pC0[6] = fadd_s(pC0[6], off); pC1[6] = fadd_s(pC1[6], off); FA_SB();
;         FA_PVM(3); ra = __builtin_fmaxf(__builtin_fmaxf(ra, pC0[5]), pC0[6]); rb = __builtin_fmaxf(__builtin_fmaxf(rb, pC1[5]), pC1[6]); pC0[7] = fadd_s(pC0[7], off); pC1[7] = fadd_s(pC1[7], off); pC0[8] = fadd_s(pC0[8], off); pC1[8] = fadd_s(pC1[8], off); FA_SB();
;         FA_PVM(4); ra = __builtin_fmaxf(__builtin_fmaxf(ra, pC0[7]), pC0[8]); rb = __builtin_fmaxf(__builtin_fmaxf(rb, pC1[7]), pC1[8]); pC0[9] = fadd_s(pC0[9], off); pC1[9] = fadd_s(pC1[9], off); pC0[10] = fadd_s(pC0[10], off); pC1[10] = fadd_s(pC1[10], off); FA_SB();
;         FA_PVM(5); ra = __builtin_fmaxf(__builtin_fmaxf(ra, pC0[9]), pC0[10]); rb = __builtin_fmaxf(__builtin_fmaxf(rb, pC1[9]), pC1[10]); pC0[11] = fadd_s(pC0[11], off); pC1[11] = fadd_s(pC1[11], off); pC0[12] = fadd_s(pC0[12], off); pC1[12] = fadd_s(pC1[12], off); FA_SB();
;         FA_PVM(6); ra = __builtin_fmaxf(__builtin_fmaxf(ra, pC0[11]), pC0[12]); rb = __builtin_fmaxf(__builtin_fmaxf(rb, pC1[11]), pC1[12]); pC0[13] = fadd_s(pC0[13], off); pC1[13] = fadd_s(pC1[13], off); pC0[14] = fadd_s(pC0[14], off); pC1[14] = fadd_s(pC1[14], off); FA_SB();
;         FA_PVM(7); ra = __builtin_fmaxf(__builtin_fmaxf(ra, pC0[13]), pC0[14]); rb = __builtin_fmaxf(__builtin_fmaxf(rb, pC1[13]), pC1[14]); pC0[15] = fadd_s(pC0[15], off); pC1[15] = fadd_s(pC1[15], off); ra = __builtin_fmaxf(__builtin_fmaxf(ra, pC0[15]), pC1[15]); rm = __builtin_fmaxf(ra, rb); FA_SB();
;         rm = xhalf_max(rm);
;         FA_SB();
;         if (first || __any(rm > 8.0f)) {
.LBB0_460:
	v_max3_f32 v96, v64, v65, v66
	v_max3_f32 v97, v80, v81, v82
	v_cvt_pk_bf16_f32 v232, v104, v105
	v_cvt_pk_bf16_f32 v233, v106, v107
	v_add_f32_e32 v98, v112, v113
	v_add_f32_e32 v212, v98, v212
	v_mfma_f32_32x32x16_bf16 v[32:47], v[132:135], v[140:143], v[32:47]
	ds_read_b128 v[132:135], v201 offset:16416
	v_max3_f32 v96, v96, v67, v68
	v_max3_f32 v97, v97, v83, v84
	v_cvt_pk_bf16_f32 v234, v108, v109
	v_cvt_pk_bf16_f32 v235, v110, v111
	v_add_f32_e32 v98, v114, v115
	v_add_f32_e32 v212, v98, v212
	s_waitcnt lgkmcnt(1)
	v_mfma_f32_32x32x16_bf16 v[16:31], v[136:139], v[140:143], v[16:31]
	ds_read_b128 v[136:139], v201 offset:21024
	v_max3_f32 v96, v96, v69, v70
	v_max3_f32 v97, v97, v85, v86
	v_add_f32_e32 v98, v116, v117
	v_add_f32_e32 v212, v98, v212
	v_mfma_f32_32x32x16_bf16 v[0:15], v[128:131], v[140:143], v[0:15]
	ds_read_b128 v[128:131], v201 offset:25632
	v_max3_f32 v96, v96, v71, v72
	v_max3_f32 v97, v97, v87, v88
	v_add_f32_e32 v98, v118, v119
	v_add_f32_e32 v212, v98, v212
	s_waitcnt lgkmcnt(1)
	v_mfma_f32_32x32x16_bf16 v[48:63], v[132:135], v[232:235], v[48:63]
	ds_read_b128 v[132:135], v201 offset:30240
	v_max3_f32 v96, v96, v73, v74
	v_max3_f32 v97, v97, v89, v90
	v_cvt_pk_bf16_f32 v140, v112, v113
	v_cvt_pk_bf16_f32 v141, v114, v115
	v_add_f32_e32 v98, v120, v121
	v_add_f32_e32 v212, v98, v212
	v_mfma_f32_32x32x16_bf16 v[32:47], v[136:139], v[232:235], v[32:47]
	ds_read_b128 v[136:139], v201 offset:16448
	v_max3_f32 v96, v96, v75, v76
	v_max3_f32 v97, v97, v91, v92
	v_cvt_pk_bf16_f32 v142, v116, v117
	v_cvt_pk_bf16_f32 v143, v118, v119
	v_add_f32_e32 v98, v122, v123
	v_add_f32_e32 v212, v98, v212
	s_waitcnt lgkmcnt(1)
	v_mfma_f32_32x32x16_bf16 v[16:31], v[128:131], v[232:235], v[16:31]
	ds_read_b128 v[128:131], v201 offset:21056
	v_max3_f32 v96, v96, v77, v78
	v_max3_f32 v97, v97, v93, v94
	v_add_f32_e32 v98, v124, v125
	v_add_f32_e32 v212, v98, v212
	v_mfma_f32_32x32x16_bf16 v[0:15], v[132:135], v[232:235], v[0:15]
	ds_read_b128 v[132:135], v201 offset:25664
	v_max3_f32 v96, v96, v97, v79
	v_max_f32_e32 v96, v96, v95
	v_add_f32_e32 v98, v126, v127
	v_add_f32_e32 v212, v98, v212
	v_cmp_lt_f32_e32 vcc, s39, v96
	s_mov_b64 s[0:1], 0
	s_cbranch_vccnz .Lresc_o
.LBB0_462:
	s_waitcnt lgkmcnt(1)
	v_mfma_f32_32x32x16_bf16 v[48:63], v[136:139], v[140:143], v[48:63]
	ds_read_b128 v[136:139], v201 offset:30272
	v_exp_f32_e32 v64, v64
	v_exp_f32_e32 v65, v65
	v_cvt_pk_bf16_f32 v232, v120, v121
	v_cvt_pk_bf16_f32 v233, v122, v123
	v_mfma_f32_32x32x16_bf16 v[32:47], v[128:131], v[140:143], v[32:47]
	ds_read_b128 v[128:131], v201 offset:16480
	v_exp_f32_e32 v66, v66
	v_exp_f32_e32 v67, v67
	v_add_f32_e32 v98, v64, v65
	v_add_f32_e32 v212, v98, v212
	v_cvt_pk_bf16_f32 v234, v124, v125
	v_cvt_pk_bf16_f32 v235, v126, v127
	s_waitcnt lgkmcnt(1)
	v_mfma_f32_32x32x16_bf16 v[16:31], v[132:135], v[140:143], v[16:31]
	ds_read_b128 v[132:135], v201 offset:21088
	v_exp_f32_e32 v68, v68
	v_exp_f32_e32 v69, v69
	v_add_f32_e32 v98, v66, v67
	v_add_f32_e32 v212, v98, v212
	v_mfma_f32_32x32x16_bf16 v[0:15], v[136:139], v[140:143], v[0:15]
	ds_read_b128 v[136:139], v201 offset:25696
	v_exp_f32_e32 v70, v70
	v_exp_f32_e32 v71, v71
	v_add_f32_e32 v98, v68, v69
	v_add_f32_e32 v212, v98, v212
	s_waitcnt lgkmcnt(1)
	v_mfma_f32_32x32x16_bf16 v[48:63], v[128:131], v[232:235], v[48:63]
	ds_read_b128 v[128:131], v201 offset:30304
	ds_read_b128 v[200:203], v247
	ds_read_b128 v[196:199], v247 offset:512
	ds_read_b128 v[192:195], v248
	ds_read_b128 v[188:191], v248 offset:512
	v_exp_f32_e32 v72, v72
	v_exp_f32_e32 v73, v73
	v_add_f32_e32 v98, v70, v71
	v_add_f32_e32 v212, v98, v212
	v_mfma_f32_32x32x16_bf16 v[32:47], v[132:135], v[232:235], v[32:47]
	v_exp_f32_e32 v74, v74
	v_exp_f32_e32 v75, v75
	v_add_f32_e32 v98, v72, v73
	v_add_f32_e32 v212, v98, v212
	s_waitcnt lgkmcnt(4)
	v_mfma_f32_32x32x16_bf16 v[16:31], v[136:139], v[232:235], v[16:31]
	v_exp_f32_e32 v76, v76
	v_exp_f32_e32 v77, v77
	v_add_f32_e32 v98, v74, v75
	v_add_f32_e32 v212, v98, v212
	v_mfma_f32_32x32x16_bf16 v[0:15], v[128:131], v[232:235], v[0:15]
	v_exp_f32_e32 v78, v78
	v_exp_f32_e32 v79, v79
	v_add_f32_e32 v98, v76, v77
	v_add_f32_e32 v212, v98, v212
	s_min_u32 s12, s34, 0x7f
	s_lshl_b32 s12, s12, 6
	s_sub_i32 s14, s12, s47
	s_sub_i32 s15, s14, 31
	s_cmpk_lt_i32 s15, 0x22f
	s_cselect_b32 s98, s100, s101
	s_cselect_b32 s15, 1, 0
	s_cmpk_gt_i32 s14, 0xfd92
	s_cselect_b32 s15, s15, 0
	s_cmp_lg_u32 s15, 0
	s_cbranch_scc1 .Lgather_o
	s_cmp_lg_u32 s99, s98
	s_cbranch_scc1 .Lz_upd_o
.Lz_go_o:
	s_waitcnt lgkmcnt(0)
	v_mfma_f32_32x32x16_bf16 v[96:111], v[200:203], v[160:163], v[144:159]
	v_exp_f32_e32 v80, v80
	v_exp_f32_e32 v81, v81
	v_add_f32_e32 v206, v78, v79
	v_add_f32_e32 v212, v206, v212
	v_mfma_f32_32x32x16_bf16 v[112:127], v[196:199], v[160:163], v[144:159]
	v_exp_f32_e32 v82, v82
	v_exp_f32_e32 v83, v83
